# P6: gMLP operand prefetch one chunk ahead (counted waits) + B2 group-start state stored directly from accumulator registers instead of an LDS read-back loop
# speedup vs baseline: 1.0015x; 1.0015x over previous
; #define LAS __attribute__((address_space(3)))
; __device__ __forceinline__ void rwkv_phase_b2(const Ctx& C) {
;     ...
;         for (int g0 = 0; g0 < NGRP; g0 += 4) {
; #pragma unroll
;             for (int s = 0; s < 4; ++s) {
;                 const int g = g0 + s; const size_t o = ob + (size_t)g * 4096;
;                 for (int e = tid; e < 1024; e += NTHR) Sg[o + (rb * 16 + (e >> 6)) * 64 + (e & 63)] = MAT(0)[(e >> 6) * MS + (e & 63)];
;                 f32x4 a0 = (f32x4){0.f, 0.f, 0.f, 0.f}, a1 = a0; float qc[4];
;                 if (w < 4) {
;                     const LAS float* m0 = MAT(0);
; #pragma unroll
;                     for (int kb = 0; kb < 4; kb += 2) {
;                         const f32x4 s0 = *(const LAS f32x4*)(m0 + l15 * MS + 16 * kb + 4 * q), s1 = *(const LAS f32x4*)(m0 + l15 * MS + 16 * (kb + 1) + 4 * q);
; #pragma unroll
;                         for (int j = 0; j < 4; ++j) {
;                             a0 = __builtin_amdgcn_mfma_f32_16x16x4f32(s0[j], pv[s][4 * kb + j], a0, 0, 0, 0);
;                             a1 = __builtin_amdgcn_mfma_f32_16x16x4f32(s1[j], pv[s][4 * (kb + 1) + j], a1, 0, 0, 0);
;                         }
;                     }
; #pragma unroll
;                     for (int j = 0; j < 4; ++j) qc[j] = qv[s][j];
;                     if (g + 4 < NGRP) {
; #pragma unroll
;                         for (int i = 0; i < 16; ++i) pv[s][i] = Pc[o + 4 * 4096 + poff + ((i & 3) + 16 * (i >> 2)) * 64];
; #pragma unroll
;                         for (int j = 0; j < 4; ++j) qv[s][j] = Qc[o + 4 * 4096 + qoff + j * 64];
;                     }
.LBB0_967:
	s_and_b32 s36, s1, 0xffffffe0
	s_lshl_b32 s35, s3, 8
	s_ashr_i32 s37, s36, 31
	s_and_b32 s35, s35, 0x3000
	s_lshl_b64 s[36:37], s[36:37], 14
	v_lshl_or_b32 v2, v37, 2, s35
	v_or_b32_e32 v2, s36, v2
	v_mov_b32_e32 v3, s37
	s_lshl_b64 s[22:23], s[22:23], 12
	v_lshl_add_u64 v[24:25], v[22:23], 0, v[2:3]
	v_lshl_add_u64 v[26:27], v[20:21], 0, v[2:3]
	v_lshl_add_u64 v[28:29], v[18:19], 0, v[2:3]
	v_lshl_add_u64 v[30:31], v[16:17], 0, v[2:3]
	s_mov_b32 s35, 0
	s_waitcnt vmcnt(0)
	v_mov_b32_e32 v113, v132
	v_mov_b32_e32 v114, v130
	v_mov_b32_e32 v115, v129
	v_mov_b32_e32 v116, v131
	v_mov_b32_e32 v121, v120
	v_mov_b32_e32 v122, v119
	v_mov_b32_e32 v123, v117
	v_mov_b32_e32 v124, v118
	v_mov_b32_e32 v129, v112
	v_mov_b32_e32 v130, v111
	v_mov_b32_e32 v131, v110
	v_mov_b32_e32 v132, v109
	v_mov_b32_e32 v117, v108
	v_mov_b32_e32 v118, v106
	v_mov_b32_e32 v119, v105
	v_mov_b32_e32 v120, v107
	s_waitcnt lgkmcnt(0)
	s_barrier
	ds_read_b32 v142, v36
	ds_read_b32 v143, v36 offset:2176
	v_lshrrev_b32_e32 v150, 4, v193
	v_mul_u32_u24_e32 v150, 0x3c0, v150
	s_mul_i32 s56, s80, 0xc0
	v_subrev_u32_e32 v150, s56, v150
	v_ashrrev_i32_e32 v151, 31, v150
	s_waitcnt lgkmcnt(0)
	global_store_dword v[30:31], v142, off
	global_store_dword v[30:31], v143, off offset:2048
.LBB0_968:
	s_lshl_b32 s36, s35, 12
	v_mov_b32_e32 v2, 0
	s_and_b64 vcc, exec, s[16:17]
	s_cbranch_vccz .LBB0_973
	ds_read_b128 v[2:5], v35
	ds_read_b128 v[6:9], v35 offset:64
	s_cmp_gt_u32 s35, 27
	v_mov_b32_e32 v105, v119
	s_waitcnt lgkmcnt(1)
	v_mfma_f32_16x16x4_f32 v[106:109], v2, v48, 0
	s_waitcnt lgkmcnt(0)
	v_mfma_f32_16x16x4_f32 v[134:137], v6, v49, 0
	v_mfma_f32_16x16x4_f32 v[106:109], v3, v41, v[106:109]
	v_mfma_f32_16x16x4_f32 v[134:137], v7, v50, v[134:137]
	v_mfma_f32_16x16x4_f32 v[106:109], v4, v42, v[106:109]
	v_mfma_f32_16x16x4_f32 v[134:137], v8, v51, v[134:137]
	v_mfma_f32_16x16x4_f32 v[2:5], v5, v43, v[106:109]
	v_mfma_f32_16x16x4_f32 v[6:9], v9, v53, v[134:137]
	s_nop 6
	ds_read_b128 v[106:109], v35 offset:128
	ds_read_b128 v[134:137], v35 offset:192
	s_waitcnt lgkmcnt(1)
	v_mfma_f32_16x16x4_f32 v[2:5], v106, v57, v[2:5]
	v_mov_b32_e32 v106, v118
	s_waitcnt lgkmcnt(0)
	v_mfma_f32_16x16x4_f32 v[6:9], v134, v44, v[6:9]
	v_mfma_f32_16x16x4_f32 v[2:5], v107, v52, v[2:5]
	v_mov_b32_e32 v107, v120
	v_mfma_f32_16x16x4_f32 v[6:9], v135, v45, v[6:9]
	v_mfma_f32_16x16x4_f32 v[2:5], v108, v54, v[2:5]
	v_mov_b32_e32 v108, v117
	v_mfma_f32_16x16x4_f32 v[6:9], v136, v46, v[6:9]
	v_mfma_f32_16x16x4_f32 v[2:5], v109, v55, v[2:5]
	v_mfma_f32_16x16x4_f32 v[6:9], v137, v47, v[6:9]
	s_cbranch_scc1 .LBB0_974
	s_add_u32 s38, s22, s36
	s_addc_u32 s39, s23, 0
	s_lshl_b64 s[38:39], s[38:39], 2
	s_add_u32 s42, s10, s38
	s_addc_u32 s43, s11, s39
	v_lshl_add_u64 v[42:43], v[10:11], 2, s[42:43]
	v_add_co_u32_e32 v108, vcc, s30, v42
	s_add_u32 s38, s12, s38
	s_nop 0
	v_addc_co_u32_e32 v109, vcc, 0, v43, vcc
	v_add_co_u32_e32 v50, vcc, s31, v42
	s_addc_u32 s39, s13, s39
	s_nop 0
	v_addc_co_u32_e32 v51, vcc, 0, v43, vcc
	v_add_co_u32_e32 v110, vcc, s33, v42
	v_lshl_add_u64 v[48:49], v[42:43], 0, s[20:21]
	s_nop 0
	v_addc_co_u32_e32 v111, vcc, 0, v43, vcc
	v_lshl_add_u64 v[42:43], v[12:13], 2, s[38:39]
	v_add_co_u32_e32 v134, vcc, 0x10000, v42
	global_load_dword v44, v[110:111], off
	global_load_dword v45, v[110:111], off offset:256
	global_load_dword v46, v[110:111], off offset:512
	global_load_dword v47, v[110:111], off offset:768
	v_lshl_add_u64 v[126:127], v[42:43], 0, s[20:21]
	v_addc_co_u32_e32 v135, vcc, 0, v43, vcc
	global_load_dword v41, v[48:49], off offset:256
	global_load_dword v42, v[48:49], off offset:512
	global_load_dword v43, v[48:49], off offset:768
	global_load_dword v52, v[50:51], off offset:256
	global_load_dword v54, v[50:51], off offset:512
	global_load_dword v55, v[50:51], off offset:768
	global_load_dword v105, v[126:127], off offset:256
	global_load_dword v106, v[126:127], off offset:512
	global_load_dword v48, v[108:109], off offset:-4096
	global_load_dword v49, v[108:109], off
	s_nop 0
	global_load_dword v50, v[108:109], off offset:256
	global_load_dword v51, v[108:109], off offset:512
	global_load_dword v53, v[108:109], off offset:768
	global_load_dword v57, v[110:111], off offset:-4096
	global_load_dword v107, v[134:135], off
	s_nop 0
	global_load_dword v108, v[126:127], off offset:768
	s_branch .LBB0_974

; #define LAS __attribute__((address_space(3)))
; __device__ __forceinline__ void rwkv_phase_b2(const Ctx& C) {
;     ...
;             for (int s = 0; s < 4; ++s) {
;                 const int g = g0 + s; const size_t o = ob + (size_t)g * 4096;
;                 for (int e = tid; e < 1024; e += NTHR) Sg[o + (rb * 16 + (e >> 6)) * 64 + (e & 63)] = MAT(0)[(e >> 6) * MS + (e & 63)];
;                 f32x4 a0 = (f32x4){0.f, 0.f, 0.f, 0.f}, a1 = a0; float qc[4];
;                 if (w < 4) {
;                     const LAS float* m0 = MAT(0);
; #pragma unroll
;                     for (int kb = 0; kb < 4; kb += 2) {
;                         const f32x4 s0 = *(const LAS f32x4*)(m0 + l15 * MS + 16 * kb + 4 * q), s1 = *(const LAS f32x4*)(m0 + l15 * MS + 16 * (kb + 1) + 4 * q);
; #pragma unroll
;                         for (int j = 0; j < 4; ++j) {
;                             a0 = __builtin_amdgcn_mfma_f32_16x16x4f32(s0[j], pv[s][4 * kb + j], a0, 0, 0, 0);
;                             a1 = __builtin_amdgcn_mfma_f32_16x16x4f32(s1[j], pv[s][4 * (kb + 1) + j], a1, 0, 0, 0);
;                         }
;                     }
; #pragma unroll
;                     for (int j = 0; j < 4; ++j) qc[j] = qv[s][j];
;                     if (g + 4 < NGRP) {
; #pragma unroll
;                         for (int i = 0; i < 16; ++i) pv[s][i] = Pc[o + 4 * 4096 + poff + ((i & 3) + 16 * (i >> 2)) * 64];
; #pragma unroll
;                         for (int j = 0; j < 4; ++j) qv[s][j] = Qc[o + 4 * 4096 + qoff + j * 64];
;                     }
;                 }
;                 __syncthreads();
;                 if (w < 4) {
; #pragma unroll
;                     for (int j = 0; j < 4; ++j) { const int r = 4 * q + j, c2 = w * 16 + l15; MAT(0)[r * MS + c2] = a0[j] + a1[j] + qc[j]; }
;                 }
;                 __syncthreads();
;             }
.LBB0_974:
	s_and_b64 vcc, exec, s[6:7]
	s_barrier
	s_cbranch_vccnz .LBB0_976
	s_nop 5
	v_add_f32_e32 v2, v2, v6
	v_add_f32_e32 v3, v3, v7
	v_add_f32_e32 v2, v120, v2
	v_add_f32_e32 v3, v119, v3
	ds_write2_b32 v39, v2, v3 offset1:68
	v_mov_b32_e32 v154, v2
	v_mov_b32_e32 v155, v3
	v_add_f32_e32 v2, v4, v8
	v_add_f32_e32 v2, v118, v2
	ds_write_b32 v39, v2 offset:544
	v_mov_b32_e32 v156, v2
	v_add_f32_e32 v2, v5, v9
	v_add_f32_e32 v2, v117, v2
	ds_write_b32 v40, v2
	v_lshl_add_u64 v[152:153], v[28:29], 0, v[150:151]
	global_store_dword v[152:153], v154, off
	global_store_dword v[152:153], v155, off offset:256
	global_store_dword v[152:153], v156, off offset:512
	global_store_dword v[152:153], v2, off offset:768
.LBB0_976:
	s_nop 3
	s_waitcnt lgkmcnt(0)
	s_barrier
	s_and_b64 vcc, exec, s[6:7]
	v_mov_b32_e32 v2, 0
	s_cbranch_vccnz .LBB0_981
	ds_read_b128 v[2:5], v35
	ds_read_b128 v[6:9], v35 offset:64
	s_cmp_gt_u32 s35, 27
	v_mov_b32_e32 v109, v132
	v_mov_b32_e32 v110, v131
	s_waitcnt lgkmcnt(1)
	v_mfma_f32_16x16x4_f32 v[134:137], v2, v64, 0
	v_mov_b32_e32 v111, v130
	v_mov_b32_e32 v112, v129
	s_waitcnt lgkmcnt(0)
	v_mfma_f32_16x16x4_f32 v[138:141], v6, v103, 0
	v_mfma_f32_16x16x4_f32 v[134:137], v3, v56, v[134:137]
	v_mfma_f32_16x16x4_f32 v[138:141], v7, v65, v[138:141]
	v_mfma_f32_16x16x4_f32 v[134:137], v4, v58, v[134:137]
	v_mfma_f32_16x16x4_f32 v[138:141], v8, v66, v[138:141]
	v_mfma_f32_16x16x4_f32 v[2:5], v5, v59, v[134:137]
	v_mfma_f32_16x16x4_f32 v[6:9], v9, v67, v[138:141]
	s_nop 6
	ds_read_b128 v[134:137], v35 offset:128
	ds_read_b128 v[138:141], v35 offset:192
	s_waitcnt lgkmcnt(1)
	v_mfma_f32_16x16x4_f32 v[2:5], v134, v104, v[2:5]
	s_waitcnt lgkmcnt(0)
	v_mfma_f32_16x16x4_f32 v[6:9], v138, v60, v[6:9]
	v_mfma_f32_16x16x4_f32 v[2:5], v135, v98, v[2:5]
	v_mfma_f32_16x16x4_f32 v[6:9], v139, v61, v[6:9]
	v_mfma_f32_16x16x4_f32 v[2:5], v136, v100, v[2:5]
	v_mfma_f32_16x16x4_f32 v[6:9], v140, v62, v[6:9]
	v_mfma_f32_16x16x4_f32 v[2:5], v137, v102, v[2:5]
	v_mfma_f32_16x16x4_f32 v[6:9], v141, v63, v[6:9]
	s_cbranch_scc1 .LBB0_982
	s_or_b32 s37, s36, 0x1000
	s_add_u32 s38, s22, s37
	s_addc_u32 s39, s23, 0
	s_lshl_b64 s[38:39], s[38:39], 2
	s_add_u32 s42, s10, s38
	s_addc_u32 s43, s11, s39
	v_lshl_add_u64 v[58:59], v[10:11], 2, s[42:43]
	v_add_co_u32_e32 v118, vcc, s30, v58
	s_add_u32 s38, s12, s38
	s_nop 0
	v_addc_co_u32_e32 v119, vcc, 0, v59, vcc
	v_add_co_u32_e32 v66, vcc, s31, v58
	s_addc_u32 s39, s13, s39
	s_nop 0
	v_addc_co_u32_e32 v67, vcc, 0, v59, vcc
	v_add_co_u32_e32 v126, vcc, s33, v58
	v_lshl_add_u64 v[64:65], v[58:59], 0, s[20:21]
	s_nop 0
	v_addc_co_u32_e32 v127, vcc, 0, v59, vcc
	v_lshl_add_u64 v[58:59], v[12:13], 2, s[38:39]
	v_add_co_u32_e32 v136, vcc, 0x10000, v58
	global_load_dword v60, v[126:127], off
	global_load_dword v61, v[126:127], off offset:256
	global_load_dword v62, v[126:127], off offset:512
	global_load_dword v63, v[126:127], off offset:768
	v_lshl_add_u64 v[134:135], v[58:59], 0, s[20:21]
	v_addc_co_u32_e32 v137, vcc, 0, v59, vcc
	global_load_dword v56, v[64:65], off offset:256
	global_load_dword v58, v[64:65], off offset:512
	global_load_dword v59, v[64:65], off offset:768
	global_load_dword v98, v[66:67], off offset:256
	global_load_dword v100, v[66:67], off offset:512
	global_load_dword v102, v[66:67], off offset:768
	global_load_dword v110, v[134:135], off offset:256
	global_load_dword v111, v[134:135], off offset:512
	global_load_dword v64, v[118:119], off offset:-4096
	global_load_dword v103, v[118:119], off
	global_load_dword v65, v[118:119], off offset:256
	global_load_dword v66, v[118:119], off offset:512
	global_load_dword v67, v[118:119], off offset:768
	global_load_dword v104, v[126:127], off offset:-4096
	global_load_dword v109, v[136:137], off
	global_load_dword v112, v[134:135], off offset:768
	s_branch .LBB0_982

; #define LAS __attribute__((address_space(3)))
; __device__ __forceinline__ void rwkv_phase_b2(const Ctx& C) {
;     ...
;             for (int s = 0; s < 4; ++s) {
;                 const int g = g0 + s; const size_t o = ob + (size_t)g * 4096;
;                 for (int e = tid; e < 1024; e += NTHR) Sg[o + (rb * 16 + (e >> 6)) * 64 + (e & 63)] = MAT(0)[(e >> 6) * MS + (e & 63)];
;                 f32x4 a0 = (f32x4){0.f, 0.f, 0.f, 0.f}, a1 = a0; float qc[4];
;                 if (w < 4) {
;                     const LAS float* m0 = MAT(0);
; #pragma unroll
;                     for (int kb = 0; kb < 4; kb += 2) {
;                         const f32x4 s0 = *(const LAS f32x4*)(m0 + l15 * MS + 16 * kb + 4 * q), s1 = *(const LAS f32x4*)(m0 + l15 * MS + 16 * (kb + 1) + 4 * q);
; #pragma unroll
;                         for (int j = 0; j < 4; ++j) {
;                             a0 = __builtin_amdgcn_mfma_f32_16x16x4f32(s0[j], pv[s][4 * kb + j], a0, 0, 0, 0);
;                             a1 = __builtin_amdgcn_mfma_f32_16x16x4f32(s1[j], pv[s][4 * (kb + 1) + j], a1, 0, 0, 0);
;                         }
;                     }
; #pragma unroll
;                     for (int j = 0; j < 4; ++j) qc[j] = qv[s][j];
;                     if (g + 4 < NGRP) {
; #pragma unroll
;                         for (int i = 0; i < 16; ++i) pv[s][i] = Pc[o + 4 * 4096 + poff + ((i & 3) + 16 * (i >> 2)) * 64];
; #pragma unroll
;                         for (int j = 0; j < 4; ++j) qv[s][j] = Qc[o + 4 * 4096 + qoff + j * 64];
;                     }
;                 }
;                 __syncthreads();
;                 if (w < 4) {
; #pragma unroll
;                     for (int j = 0; j < 4; ++j) { const int r = 4 * q + j, c2 = w * 16 + l15; MAT(0)[r * MS + c2] = a0[j] + a1[j] + qc[j]; }
;                 }
;                 __syncthreads();
;             }
.LBB0_982:
	s_and_b64 vcc, exec, s[6:7]
	s_barrier
	s_cbranch_vccnz .LBB0_984
	s_nop 5
	v_add_f32_e32 v2, v2, v6
	v_add_f32_e32 v3, v3, v7
	v_add_f32_e32 v2, v132, v2
	v_add_f32_e32 v3, v131, v3
	ds_write2_b32 v39, v2, v3 offset1:68
	v_mov_b32_e32 v154, v2
	v_mov_b32_e32 v155, v3
	v_add_f32_e32 v2, v4, v8
	v_add_f32_e32 v2, v130, v2
	ds_write_b32 v39, v2 offset:544
	v_mov_b32_e32 v156, v2
	v_add_f32_e32 v2, v5, v9
	v_add_f32_e32 v2, v129, v2
	ds_write_b32 v40, v2
	v_lshl_add_u64 v[152:153], v[26:27], 0, v[150:151]
	global_store_dword v[152:153], v154, off
	global_store_dword v[152:153], v155, off offset:256
	global_store_dword v[152:153], v156, off offset:512
	global_store_dword v[152:153], v2, off offset:768
.LBB0_984:
	s_nop 3
	s_waitcnt lgkmcnt(0)
	s_barrier
	s_and_b64 vcc, exec, s[6:7]
	v_mov_b32_e32 v2, 0
	s_cbranch_vccnz .LBB0_989
	ds_read_b128 v[2:5], v35
	ds_read_b128 v[6:9], v35 offset:64
	s_cmp_gt_u32 s35, 27
	v_mov_b32_e32 v118, v124
	v_mov_b32_e32 v117, v123
	s_waitcnt lgkmcnt(1)
	v_mfma_f32_16x16x4_f32 v[126:129], v2, v75, 0
	v_mov_b32_e32 v119, v122
	v_mov_b32_e32 v120, v121
	s_waitcnt lgkmcnt(0)
	v_mfma_f32_16x16x4_f32 v[130:133], v6, v99, 0
	v_mfma_f32_16x16x4_f32 v[126:129], v3, v69, v[126:129]
	v_mfma_f32_16x16x4_f32 v[130:133], v7, v76, v[130:133]
	v_mfma_f32_16x16x4_f32 v[126:129], v4, v71, v[126:129]
	v_mfma_f32_16x16x4_f32 v[130:133], v8, v77, v[130:133]
	v_mfma_f32_16x16x4_f32 v[2:5], v5, v73, v[126:129]
	v_mfma_f32_16x16x4_f32 v[6:9], v9, v78, v[130:133]
	s_nop 6
	ds_read_b128 v[126:129], v35 offset:128
	ds_read_b128 v[130:133], v35 offset:192
	s_waitcnt lgkmcnt(1)
	v_mfma_f32_16x16x4_f32 v[2:5], v126, v101, v[2:5]
	s_waitcnt lgkmcnt(0)
	v_mfma_f32_16x16x4_f32 v[6:9], v130, v68, v[6:9]
	v_mfma_f32_16x16x4_f32 v[2:5], v127, v92, v[2:5]
	v_mfma_f32_16x16x4_f32 v[6:9], v131, v70, v[6:9]
	v_mfma_f32_16x16x4_f32 v[2:5], v128, v94, v[2:5]
	v_mfma_f32_16x16x4_f32 v[6:9], v132, v72, v[6:9]
	v_mfma_f32_16x16x4_f32 v[2:5], v129, v95, v[2:5]
	v_mfma_f32_16x16x4_f32 v[6:9], v133, v74, v[6:9]
	s_cbranch_scc1 .LBB0_990
	s_or_b32 s37, s36, 0x2000
	s_add_u32 s38, s22, s37
	s_addc_u32 s39, s23, 0
	s_lshl_b64 s[38:39], s[38:39], 2
	s_add_u32 s42, s10, s38
	s_addc_u32 s43, s11, s39
	v_lshl_add_u64 v[68:69], v[10:11], 2, s[42:43]
	v_add_co_u32_e32 v126, vcc, s30, v68
	s_add_u32 s38, s12, s38
	s_nop 0
	v_addc_co_u32_e32 v127, vcc, 0, v69, vcc
	v_add_co_u32_e32 v118, vcc, s31, v68
	s_addc_u32 s39, s13, s39
	s_nop 0
	v_addc_co_u32_e32 v119, vcc, 0, v69, vcc
	v_add_co_u32_e32 v128, vcc, s33, v68
	v_lshl_add_u64 v[94:95], v[12:13], 2, s[38:39]
	s_nop 0
	v_addc_co_u32_e32 v129, vcc, 0, v69, vcc
	v_lshl_add_u64 v[76:77], v[68:69], 0, s[20:21]
	v_add_co_u32_e32 v132, vcc, 0x10000, v94
	global_load_dword v68, v[128:129], off
	global_load_dword v70, v[128:129], off offset:256
	global_load_dword v72, v[128:129], off offset:512
	global_load_dword v74, v[128:129], off offset:768
	v_lshl_add_u64 v[130:131], v[94:95], 0, s[20:21]
	v_addc_co_u32_e32 v133, vcc, 0, v95, vcc
	global_load_dword v69, v[76:77], off offset:256
	global_load_dword v71, v[76:77], off offset:512
	global_load_dword v73, v[76:77], off offset:768
	global_load_dword v92, v[118:119], off offset:256
	global_load_dword v94, v[118:119], off offset:512
	global_load_dword v95, v[118:119], off offset:768
	global_load_dword v117, v[130:131], off offset:256
	s_nop 0
	global_load_dword v119, v[130:131], off offset:512
	global_load_dword v75, v[126:127], off offset:-4096
	global_load_dword v99, v[126:127], off
	global_load_dword v76, v[126:127], off offset:256
	global_load_dword v77, v[126:127], off offset:512
	global_load_dword v78, v[126:127], off offset:768
	global_load_dword v101, v[128:129], off offset:-4096
	global_load_dword v118, v[132:133], off
	global_load_dword v120, v[130:131], off offset:768
	s_branch .LBB0_990

; #define LAS __attribute__((address_space(3)))
; __device__ __forceinline__ void rwkv_phase_b2(const Ctx& C) {
;     ...
;             for (int s = 0; s < 4; ++s) {
;                 const int g = g0 + s; const size_t o = ob + (size_t)g * 4096;
;                 for (int e = tid; e < 1024; e += NTHR) Sg[o + (rb * 16 + (e >> 6)) * 64 + (e & 63)] = MAT(0)[(e >> 6) * MS + (e & 63)];
;                 f32x4 a0 = (f32x4){0.f, 0.f, 0.f, 0.f}, a1 = a0; float qc[4];
;                 if (w < 4) {
;                     const LAS float* m0 = MAT(0);
; #pragma unroll
;                     for (int kb = 0; kb < 4; kb += 2) {
;                         const f32x4 s0 = *(const LAS f32x4*)(m0 + l15 * MS + 16 * kb + 4 * q), s1 = *(const LAS f32x4*)(m0 + l15 * MS + 16 * (kb + 1) + 4 * q);
; #pragma unroll
;                         for (int j = 0; j < 4; ++j) {
;                             a0 = __builtin_amdgcn_mfma_f32_16x16x4f32(s0[j], pv[s][4 * kb + j], a0, 0, 0, 0);
;                             a1 = __builtin_amdgcn_mfma_f32_16x16x4f32(s1[j], pv[s][4 * (kb + 1) + j], a1, 0, 0, 0);
;                         }
;                     }
; #pragma unroll
;                     for (int j = 0; j < 4; ++j) qc[j] = qv[s][j];
;                     if (g + 4 < NGRP) {
; #pragma unroll
;                         for (int i = 0; i < 16; ++i) pv[s][i] = Pc[o + 4 * 4096 + poff + ((i & 3) + 16 * (i >> 2)) * 64];
; #pragma unroll
;                         for (int j = 0; j < 4; ++j) qv[s][j] = Qc[o + 4 * 4096 + qoff + j * 64];
;                     }
.LBB0_990:
	s_and_b64 vcc, exec, s[6:7]
	s_barrier
	s_cbranch_vccnz .LBB0_992
	s_nop 5
	v_add_f32_e32 v2, v2, v6
	v_add_f32_e32 v3, v3, v7
	v_add_f32_e32 v2, v124, v2
	v_add_f32_e32 v3, v123, v3
	ds_write2_b32 v39, v2, v3 offset1:68
	v_mov_b32_e32 v154, v2
	v_mov_b32_e32 v155, v3
	v_add_f32_e32 v2, v4, v8
	v_add_f32_e32 v2, v122, v2
	ds_write_b32 v39, v2 offset:544
	v_mov_b32_e32 v156, v2
	v_add_f32_e32 v2, v5, v9
	v_add_f32_e32 v2, v121, v2
	ds_write_b32 v40, v2
	v_lshl_add_u64 v[152:153], v[24:25], 0, v[150:151]
	global_store_dword v[152:153], v154, off
	global_store_dword v[152:153], v155, off offset:256
	global_store_dword v[152:153], v156, off offset:512
	global_store_dword v[152:153], v2, off offset:768
.LBB0_992:
	s_nop 3
	s_waitcnt lgkmcnt(0)
	s_barrier
	s_and_b64 vcc, exec, s[6:7]
	v_mov_b32_e32 v2, 0
	s_cbranch_vccnz .LBB0_998
	ds_read_b128 v[2:5], v35
	ds_read_b128 v[6:9], v35 offset:64
	s_cmp_gt_u32 s35, 27
	s_waitcnt lgkmcnt(1)
	v_mfma_f32_16x16x4_f32 v[122:125], v2, v89, 0
	s_waitcnt lgkmcnt(0)
	v_mfma_f32_16x16x4_f32 v[126:129], v6, v93, 0
	v_mfma_f32_16x16x4_f32 v[122:125], v3, v79, v[122:125]
	v_mfma_f32_16x16x4_f32 v[126:129], v7, v90, v[126:129]
	v_mfma_f32_16x16x4_f32 v[122:125], v4, v80, v[122:125]
	v_mfma_f32_16x16x4_f32 v[126:129], v8, v91, v[126:129]
	v_mfma_f32_16x16x4_f32 v[2:5], v5, v81, v[122:125]
	s_nop 7
	ds_read_b128 v[122:125], v35 offset:128
	ds_read_b128 v[130:133], v35 offset:192
	v_mfma_f32_16x16x4_f32 v[6:9], v9, v97, v[126:129]
	v_mov_b32_e32 v129, v115
	s_waitcnt lgkmcnt(1)
	v_mfma_f32_16x16x4_f32 v[2:5], v122, v96, v[2:5]
	s_waitcnt lgkmcnt(0)
	v_mfma_f32_16x16x4_f32 v[6:9], v130, v82, v[6:9]
	v_mov_b32_e32 v130, v114
	v_mfma_f32_16x16x4_f32 v[2:5], v123, v86, v[2:5]
	v_mfma_f32_16x16x4_f32 v[6:9], v131, v83, v[6:9]
	v_mov_b32_e32 v131, v116
	v_mfma_f32_16x16x4_f32 v[2:5], v124, v87, v[2:5]
	v_mfma_f32_16x16x4_f32 v[6:9], v132, v84, v[6:9]
	v_mov_b32_e32 v132, v113
	v_mfma_f32_16x16x4_f32 v[2:5], v125, v88, v[2:5]
	v_mfma_f32_16x16x4_f32 v[6:9], v133, v85, v[6:9]
	s_cbranch_scc1 .LBB0_997
	s_or_b32 s36, s36, 0x3000
	s_add_u32 s36, s22, s36
	s_addc_u32 s37, s23, 0
	s_lshl_b64 s[36:37], s[36:37], 2
	s_add_u32 s38, s10, s36
	s_addc_u32 s39, s11, s37
	v_lshl_add_u64 v[80:81], v[10:11], 2, s[38:39]
	v_add_co_u32_e32 v96, vcc, s30, v80
	s_add_u32 s36, s12, s36
	s_nop 0
	v_addc_co_u32_e32 v97, vcc, 0, v81, vcc
	v_add_co_u32_e32 v88, vcc, s31, v80
	s_addc_u32 s37, s13, s37
	s_nop 0
	v_addc_co_u32_e32 v89, vcc, 0, v81, vcc
	v_add_co_u32_e32 v122, vcc, s33, v80
	v_lshl_add_u64 v[86:87], v[80:81], 0, s[20:21]
	s_nop 0
	v_addc_co_u32_e32 v123, vcc, 0, v81, vcc
	v_lshl_add_u64 v[80:81], v[12:13], 2, s[36:37]
	v_add_co_u32_e32 v126, vcc, 0x10000, v80
	global_load_dword v82, v[122:123], off
	global_load_dword v83, v[122:123], off offset:256
	global_load_dword v84, v[122:123], off offset:512
	global_load_dword v85, v[122:123], off offset:768
	v_lshl_add_u64 v[124:125], v[80:81], 0, s[20:21]
	v_addc_co_u32_e32 v127, vcc, 0, v81, vcc
	global_load_dword v79, v[86:87], off offset:256
	global_load_dword v80, v[86:87], off offset:512
	global_load_dword v81, v[86:87], off offset:768
	s_nop 0
	global_load_dword v86, v[88:89], off offset:256
	global_load_dword v87, v[88:89], off offset:512
	s_nop 0
	global_load_dword v88, v[88:89], off offset:768
	s_nop 0
	global_load_dword v129, v[124:125], off offset:256
	global_load_dword v130, v[124:125], off offset:512
	global_load_dword v89, v[96:97], off offset:-4096
	global_load_dword v93, v[96:97], off
	global_load_dword v90, v[96:97], off offset:256
	global_load_dword v91, v[96:97], off offset:512
	s_nop 0
	global_load_dword v97, v[96:97], off offset:768
	s_nop 0
	global_load_dword v96, v[122:123], off offset:-4096
	global_load_dword v131, v[126:127], off
	global_load_dword v132, v[124:125], off offset:768

; __device__ __forceinline__ void rwkv_phase_b2(const Ctx& C) {
;     ...
;                 __syncthreads();
;                 if (w < 4) {
; #pragma unroll
;                     for (int j = 0; j < 4; ++j) { const int r = 4 * q + j, c2 = w * 16 + l15; MAT(0)[r * MS + c2] = a0[j] + a1[j] + qc[j]; }
;                 }
;                 __syncthreads();
;             }
.LBB0_999:
	s_and_b64 vcc, exec, s[6:7]
	s_waitcnt vmcnt(63) expcnt(7) lgkmcnt(15)
	s_barrier
	s_cbranch_vccnz .LBB0_1001
	v_add_f32_e32 v2, v2, v6
	v_add_f32_e32 v3, v3, v7
	v_add_f32_e32 v2, v128, v2
	v_add_f32_e32 v3, v127, v3
	ds_write2_b32 v39, v2, v3 offset1:68
	v_mov_b32_e32 v154, v2
	v_mov_b32_e32 v155, v3
	v_add_f32_e32 v2, v4, v8
	v_add_f32_e32 v2, v126, v2
	ds_write_b32 v39, v2 offset:544
	v_mov_b32_e32 v156, v2
	v_add_f32_e32 v2, v5, v9
	v_add_f32_e32 v2, v125, v2
	ds_write_b32 v40, v2
	s_cmp_gt_u32 s35, 27
	s_cbranch_scc1 .Lmy_b2_nostore
	v_lshl_add_u64 v[152:153], v[30:31], 0, s[20:21]
	v_lshl_add_u64 v[152:153], v[152:153], 0, v[150:151]
	global_store_dword v[152:153], v154, off
	global_store_dword v[152:153], v155, off offset:256
	global_store_dword v[152:153], v156, off offset:512
	global_store_dword v[152:153], v2, off offset:768
.Lmy_b2_nostore:
.LBB0_1001:
	s_add_i32 s36, s35, 4
	v_lshl_add_u64 v[30:31], v[30:31], 0, s[20:21]
	v_lshl_add_u64 v[28:29], v[28:29], 0, s[20:21]
	v_lshl_add_u64 v[26:27], v[26:27], 0, s[20:21]
	s_cmp_gt_u32 s35, 27
	v_lshl_add_u64 v[24:25], v[24:25], 0, s[20:21]
	s_waitcnt lgkmcnt(0)
	s_barrier
	s_cbranch_scc1 .LBB0_958
	s_waitcnt vmcnt(4)
	v_mov_b32_e32 v113, v132
	v_mov_b32_e32 v114, v130
	v_mov_b32_e32 v115, v129
	v_mov_b32_e32 v116, v131
	v_mov_b32_e32 v121, v120
	v_mov_b32_e32 v122, v119
	v_mov_b32_e32 v123, v117
	v_mov_b32_e32 v124, v118
	v_mov_b32_e32 v129, v112
	v_mov_b32_e32 v130, v111
	v_mov_b32_e32 v131, v110
	v_mov_b32_e32 v132, v109
	v_mov_b32_e32 v117, v108
	v_mov_b32_e32 v118, v106
	v_mov_b32_e32 v119, v105
	v_mov_b32_e32 v120, v107
	s_mov_b32 s35, s36
	s_branch .LBB0_968
